# saddr LDS-DMA + 4 early MFMAs per compute segment + FNORM loop without store-ack wait + mLSTM-out state loads kept in flight + 64-bit accumulator zeroing
# speedup vs baseline: 1.0049x; 1.0049x over previous
; #define PG8_LAS __attribute__((address_space(3)))
;     __device__ __forceinline__ void stage(const Unit& u, PG8_LAS unsigned char* area, int wr, int lane) const {
;         const float* src = rs + u.pm * BM + wr * 64 + lane;
;         __builtin_amdgcn_global_load_lds((const unsigned*)src, (PG8_LAS unsigned*)area, 4, 0, 0);
;         __builtin_amdgcn_global_load_lds((const unsigned*)(src + HALF), (PG8_LAS unsigned*)(area + 256), 4, 0, 0);
;     }
; template <class Epi, class Sched, bool ALIGN_EPI = false, bool SP2 = false, bool ABLK = false, bool BBLK = false>
; __device__ __forceinline__ void gemm_phase(PG8_LAS unsigned char* lds, const Gemm g, const Sched& S, const Epi& E) {
;     ...
; #pragma unroll
;         for (int a = 0; a < 2; ++a)
; #pragma unroll
;             for (int b = 0; b < 2; ++b)
; #pragma unroll
;                 for (int m = 0; m < 4; ++m)
; #pragma unroll
;                     for (int n = 0; n < 2; ++n) acc[a][b][m][n] = (f32x4){0.f, 0.f, 0.f, 0.f};
;         cur = nxt; cA = nA; cB = nB; ++ui;
.LBB0_184:
	s_lshl_b32 s10, s18, 8
	s_ashr_i32 s11, s10, 31
	s_mov_b32 m0, s64
	v_lshl_add_u64 v[4:5], s[10:11], 2, v[144:145]
	global_load_lds_dword v[4:5], off
	v_lshl_add_u64 v[4:5], v[4:5], 0, s[90:91]
	s_add_i32 m0, s64, 0x100
	s_ashr_i32 s9, s8, 31
	global_load_lds_dword v[4:5], off
	s_lshl_b64 s[10:11], s[8:9], 20
	v_readlane_b32 s16, v252, 27
	v_readlane_b32 s17, v252, 28
	s_add_u32 s10, s16, s10
	s_addc_u32 s11, s17, s11
	s_and_b64 s[16:17], s[2:3], exec
	s_cselect_b32 s9, s11, s21
	s_cselect_b32 s70, s10, s20
	s_ashr_i32 s7, s6, 31
	s_lshl_b64 s[16:17], s[6:7], 20
	s_add_u32 s16, s29, s16
	s_addc_u32 s17, s30, s17
	s_and_b64 s[24:25], s[2:3], exec
	s_cselect_b32 s7, s17, s23
	s_cselect_b32 s71, s16, s22
	s_add_u32 s20, s20, 0xc000
	s_addc_u32 s21, s21, 0
	s_add_u32 s77, s22, 0x10000
	v_mov_b32_e32 v4, 0
	s_addc_u32 vcc_lo, s23, 0
	s_mov_b32 vcc_hi, -2
	v_mov_b32_e32 v5, v4
	v_mov_b64_e32 v[6:7], 0
	v_mov_b64_e32 v[8:9], 0
	v_mov_b64_e32 v[10:11], 0
	v_mov_b64_e32 v[20:21], 0
	v_mov_b64_e32 v[22:23], 0
	v_mov_b64_e32 v[24:25], 0
	v_mov_b64_e32 v[26:27], 0
	v_mov_b64_e32 v[40:41], 0
	v_mov_b64_e32 v[42:43], 0
	v_mov_b64_e32 v[44:45], 0
	v_mov_b64_e32 v[46:47], 0
	v_mov_b64_e32 v[56:57], 0
	v_mov_b64_e32 v[58:59], 0
	v_mov_b64_e32 v[60:61], 0
	v_mov_b64_e32 v[62:63], 0
	v_mov_b64_e32 v[12:13], 0
	v_mov_b64_e32 v[14:15], 0
	v_mov_b64_e32 v[16:17], 0
	v_mov_b64_e32 v[18:19], 0
	v_mov_b64_e32 v[28:29], 0
	v_mov_b64_e32 v[30:31], 0
	v_mov_b64_e32 v[32:33], 0
	v_mov_b64_e32 v[34:35], 0
	v_mov_b64_e32 v[48:49], 0
	v_mov_b64_e32 v[50:51], 0
	v_mov_b64_e32 v[52:53], 0
	v_mov_b64_e32 v[54:55], 0
	v_mov_b64_e32 v[64:65], 0
	v_mov_b64_e32 v[66:67], 0
	v_mov_b64_e32 v[68:69], 0
	v_mov_b64_e32 v[70:71], 0
	v_mov_b64_e32 v[72:73], 0
	v_mov_b64_e32 v[74:75], 0
	v_mov_b64_e32 v[76:77], 0
	v_mov_b64_e32 v[78:79], 0
	v_mov_b64_e32 v[88:89], 0
	v_mov_b64_e32 v[90:91], 0
	v_mov_b64_e32 v[92:93], 0
	v_mov_b64_e32 v[94:95], 0
	v_mov_b64_e32 v[104:105], 0
	v_mov_b64_e32 v[106:107], 0
	v_mov_b64_e32 v[108:109], 0
	v_mov_b64_e32 v[110:111], 0
	v_mov_b64_e32 v[120:121], 0
	v_mov_b64_e32 v[122:123], 0
	v_mov_b64_e32 v[124:125], 0
	v_mov_b64_e32 v[126:127], 0
	v_mov_b64_e32 v[80:81], 0
	v_mov_b64_e32 v[82:83], 0
	v_mov_b64_e32 v[84:85], 0
	v_mov_b64_e32 v[86:87], 0
	v_mov_b64_e32 v[96:97], 0
	v_mov_b64_e32 v[98:99], 0
	v_mov_b64_e32 v[100:101], 0
	v_mov_b64_e32 v[102:103], 0
	v_mov_b64_e32 v[112:113], 0
	v_mov_b64_e32 v[114:115], 0
	v_mov_b64_e32 v[116:117], 0
	v_mov_b64_e32 v[118:119], 0
	v_mov_b64_e32 v[128:129], 0
	v_mov_b64_e32 v[130:131], 0
	v_mov_b64_e32 v[132:133], 0
	v_mov_b64_e32 v[134:135], 0

; template <class Epi, class Sched, bool ALIGN_EPI = false, bool SP2 = false, bool ABLK = false, bool BBLK = false>
; __device__ __forceinline__ void gemm_phase(PG8_LAS unsigned char* lds, const Gemm g, const Sched& S, const Epi& E) {
;     ...
; #pragma unroll
;         for (int a = 0; a < 2; ++a)
; #pragma unroll
;             for (int b = 0; b < 2; ++b)
; #pragma unroll
;                 for (int m = 0; m < 4; ++m)
; #pragma unroll
;                     for (int n = 0; n < 2; ++n) acc[a][b][m][n] = (f32x4){0.f, 0.f, 0.f, 0.f};
;         cur = nxt; cA = nA; cB = nB; ++ui;
.LBB0_438:
	s_add_u32 s10, s10, 0xc000
	s_addc_u32 s11, s11, 0
	s_add_u32 vcc_lo, s16, 0x10000
	v_mov_b32_e32 v4, 0
	s_addc_u32 vcc_hi, s17, 0
	s_mov_b32 s13, -2
	v_mov_b32_e32 v5, v4
	v_mov_b64_e32 v[6:7], 0
	v_mov_b64_e32 v[8:9], 0
	v_mov_b64_e32 v[10:11], 0
	v_mov_b64_e32 v[12:13], 0
	v_mov_b64_e32 v[14:15], 0
	v_mov_b64_e32 v[16:17], 0
	v_mov_b64_e32 v[18:19], 0
	v_mov_b64_e32 v[28:29], 0
	v_mov_b64_e32 v[30:31], 0
	v_mov_b64_e32 v[32:33], 0
	v_mov_b64_e32 v[34:35], 0
	v_mov_b64_e32 v[48:49], 0
	v_mov_b64_e32 v[50:51], 0
	v_mov_b64_e32 v[52:53], 0
	v_mov_b64_e32 v[54:55], 0
	v_mov_b64_e32 v[20:21], 0
	v_mov_b64_e32 v[22:23], 0
	v_mov_b64_e32 v[24:25], 0
	v_mov_b64_e32 v[26:27], 0
	v_mov_b64_e32 v[40:41], 0
	v_mov_b64_e32 v[42:43], 0
	v_mov_b64_e32 v[44:45], 0
	v_mov_b64_e32 v[46:47], 0
	v_mov_b64_e32 v[56:57], 0
	v_mov_b64_e32 v[58:59], 0
	v_mov_b64_e32 v[60:61], 0
	v_mov_b64_e32 v[62:63], 0
	v_mov_b64_e32 v[64:65], 0
	v_mov_b64_e32 v[66:67], 0
	v_mov_b64_e32 v[68:69], 0
	v_mov_b64_e32 v[70:71], 0
	v_mov_b64_e32 v[72:73], 0
	v_mov_b64_e32 v[74:75], 0
	v_mov_b64_e32 v[76:77], 0
	v_mov_b64_e32 v[78:79], 0
	v_mov_b64_e32 v[80:81], 0
	v_mov_b64_e32 v[82:83], 0
	v_mov_b64_e32 v[84:85], 0
	v_mov_b64_e32 v[86:87], 0
	v_mov_b64_e32 v[96:97], 0
	v_mov_b64_e32 v[98:99], 0
	v_mov_b64_e32 v[100:101], 0
	v_mov_b64_e32 v[102:103], 0
	v_mov_b64_e32 v[112:113], 0
	v_mov_b64_e32 v[114:115], 0
	v_mov_b64_e32 v[116:117], 0
	v_mov_b64_e32 v[118:119], 0
	v_mov_b64_e32 v[88:89], 0
	v_mov_b64_e32 v[90:91], 0
	v_mov_b64_e32 v[92:93], 0
	v_mov_b64_e32 v[94:95], 0
	v_mov_b64_e32 v[104:105], 0
	v_mov_b64_e32 v[106:107], 0
	v_mov_b64_e32 v[108:109], 0
	v_mov_b64_e32 v[110:111], 0
	v_mov_b64_e32 v[120:121], 0
	v_mov_b64_e32 v[122:123], 0
	v_mov_b64_e32 v[124:125], 0
	v_mov_b64_e32 v[126:127], 0
	v_mov_b64_e32 v[128:129], 0
	v_mov_b64_e32 v[130:131], 0
	v_mov_b64_e32 v[132:133], 0
	v_mov_b64_e32 v[134:135], 0

; __device__ __forceinline__ void ph_norm(const bf16_t* xin, const bf16_t* h, float scale, const float* ga, bf16_t* xout16, float* xout32, float* rsq) {
;     ...
;     for (int row = gw; row < M; row += NGW) {
;         u32x4 xw[4], hw[4];
; #pragma unroll
;         for (int jx = 0; jx < 4; ++jx) { xw[jx] = xn[jx]; hw[jx] = hn[jx]; }
;         const int nrow = row + NGW;
;         if (nrow < M) { const u32x4* xr = (const u32x4*)(xin + XB_OFF(nrow, lane)); const u32x4* hr = (const u32x4*)(h + (size_t)nrow * DM) + lane;
; #pragma unroll
;             for (int jx = 0; jx < 4; ++jx) { xn[jx] = xr[XB_JSTEP * jx]; hn[jx] = __builtin_nontemporal_load(hr + 64 * jx); } }
.LBB0_673:
	s_and_b64 s[0:1], exec, s[0:1]
	s_waitcnt vmcnt(6)
	v_mov_b64_e32 v[102:103], v[42:43]
	s_waitcnt vmcnt(5)
	v_mov_b64_e32 v[94:95], v[50:51]
	s_waitcnt vmcnt(4)
	v_mov_b64_e32 v[90:91], v[54:55]
	s_waitcnt vmcnt(5)
	v_mov_b64_e32 v[86:87], v[62:63]
	v_mov_b64_e32 v[98:99], v[46:47]
	v_mov_b64_e32 v[82:83], v[66:67]
	v_mov_b64_e32 v[78:79], v[58:59]
	v_mov_b64_e32 v[74:75], v[70:71]
	s_or_b64 s[18:19], s[0:1], s[18:19]
	v_lshl_add_u64 v[112:113], v[112:113], 0, s[20:21]
	v_lshl_add_u64 v[114:115], v[114:115], 0, s[22:23]
	v_lshl_add_u64 v[116:117], v[116:117], 0, s[24:25]
	v_mov_b64_e32 v[100:101], v[40:41]
	v_mov_b64_e32 v[92:93], v[48:49]
	v_mov_b64_e32 v[88:89], v[52:53]
	v_mov_b64_e32 v[84:85], v[60:61]
	v_mov_b64_e32 v[96:97], v[44:45]
	v_mov_b64_e32 v[80:81], v[64:65]
	v_mov_b64_e32 v[76:77], v[56:57]
	v_mov_b64_e32 v[72:73], v[68:69]
	v_mov_b32_e32 v108, v109
	s_andn2_b64 exec, exec, s[18:19]
	s_cbranch_execz .LBB0_682

; #define PG8_LAS __attribute__((address_space(3)))
;     __device__ __forceinline__ void stage(const Unit& u, PG8_LAS unsigned char* area, int wr, int lane) const {
;         if (rs) { const float* src = rs + u.pm * BM + wr * 64 + lane;
;             __builtin_amdgcn_global_load_lds((const unsigned*)src, (PG8_LAS unsigned*)area, 4, 0, 0);
;             __builtin_amdgcn_global_load_lds((const unsigned*)(src + HALF), (PG8_LAS unsigned*)(area + 256), 4, 0, 0); }
;     }
; template <class Epi, class Sched, bool ALIGN_EPI = false, bool SP2 = false, bool ABLK = false, bool BBLK = false>
; __device__ __forceinline__ void gemm_phase(PG8_LAS unsigned char* lds, const Gemm g, const Sched& S, const Epi& E) {
;     ...
; #pragma unroll
;         for (int a = 0; a < 2; ++a)
; #pragma unroll
;             for (int b = 0; b < 2; ++b)
; #pragma unroll
;                 for (int m = 0; m < 4; ++m)
; #pragma unroll
;                     for (int n = 0; n < 2; ++n) acc[a][b][m][n] = (f32x4){0.f, 0.f, 0.f, 0.f};
;         cur = nxt; cA = nA; cB = nB; ++ui;
.LBB0_915:
	s_lshl_b32 s18, s0, 8
	s_ashr_i32 s19, s18, 31
	s_mov_b32 m0, s63
	v_lshl_add_u64 v[4:5], s[18:19], 2, v[144:145]
	v_lshl_add_u64 v[6:7], v[4:5], 0, s[90:91]
	global_load_lds_dword v[4:5], off
	s_add_i32 m0, s63, 0x100
	s_mov_b32 s0, s1
	global_load_lds_dword v[6:7], off
	s_ashr_i32 s1, s1, 31
	s_lshl_b64 s[10:11], s[0:1], 20
	v_readlane_b32 s16, v252, 27
	v_readlane_b32 s17, v252, 28
	s_add_u32 s10, s16, s10
	s_addc_u32 s11, s17, s11
	s_and_b64 s[16:17], s[2:3], exec
	s_cselect_b32 s1, s11, s21
	s_cselect_b32 s19, s10, s20
	s_ashr_i32 s9, s8, 31
	s_lshl_b64 s[16:17], s[8:9], 20
	v_readlane_b32 s24, v254, 5
	v_readlane_b32 s25, v254, 6
	s_add_u32 s16, s24, s16
	s_addc_u32 s17, s25, s17
	s_and_b64 s[24:25], s[2:3], exec
	s_cselect_b32 s9, s17, s23
	s_cselect_b32 s65, s16, s22
	s_add_u32 s20, s20, 0xc000
	s_addc_u32 s21, s21, 0
	s_add_u32 s70, s22, 0x10000
	v_mov_b32_e32 v4, 0
	s_addc_u32 s71, s23, 0
	s_mov_b32 s13, -2
	v_mov_b32_e32 v5, v4
	v_mov_b64_e32 v[6:7], 0
	v_mov_b64_e32 v[8:9], 0
	v_mov_b64_e32 v[10:11], 0
	v_mov_b64_e32 v[12:13], 0
	v_mov_b64_e32 v[14:15], 0
	v_mov_b64_e32 v[20:21], 0
	v_mov_b64_e32 v[22:23], 0
	v_mov_b64_e32 v[28:29], 0
	v_mov_b64_e32 v[30:31], 0
	v_mov_b64_e32 v[40:41], 0
	v_mov_b64_e32 v[42:43], 0
	v_mov_b64_e32 v[48:49], 0
	v_mov_b64_e32 v[50:51], 0
	v_mov_b64_e32 v[56:57], 0
	v_mov_b64_e32 v[58:59], 0
	v_mov_b64_e32 v[16:17], 0
	v_mov_b64_e32 v[18:19], 0
	v_mov_b64_e32 v[24:25], 0
	v_mov_b64_e32 v[26:27], 0
	v_mov_b64_e32 v[32:33], 0
	v_mov_b64_e32 v[34:35], 0
	v_mov_b64_e32 v[44:45], 0
	v_mov_b64_e32 v[46:47], 0
	v_mov_b64_e32 v[52:53], 0
	v_mov_b64_e32 v[54:55], 0
	v_mov_b64_e32 v[60:61], 0
	v_mov_b64_e32 v[62:63], 0
	v_mov_b64_e32 v[64:65], 0
	v_mov_b64_e32 v[66:67], 0
	v_mov_b64_e32 v[68:69], 0
	v_mov_b64_e32 v[70:71], 0
	v_mov_b64_e32 v[72:73], 0
	v_mov_b64_e32 v[74:75], 0
	v_mov_b64_e32 v[76:77], 0
	v_mov_b64_e32 v[78:79], 0
	v_mov_b64_e32 v[80:81], 0
	v_mov_b64_e32 v[82:83], 0
	v_mov_b64_e32 v[88:89], 0
	v_mov_b64_e32 v[90:91], 0
	v_mov_b64_e32 v[96:97], 0
	v_mov_b64_e32 v[98:99], 0
	v_mov_b64_e32 v[104:105], 0
	v_mov_b64_e32 v[106:107], 0
	v_mov_b64_e32 v[112:113], 0
	v_mov_b64_e32 v[114:115], 0
	v_mov_b64_e32 v[120:121], 0
	v_mov_b64_e32 v[122:123], 0
	v_mov_b64_e32 v[84:85], 0
	v_mov_b64_e32 v[86:87], 0
	v_mov_b64_e32 v[92:93], 0
	v_mov_b64_e32 v[94:95], 0
	v_mov_b64_e32 v[100:101], 0
	v_mov_b64_e32 v[102:103], 0
	v_mov_b64_e32 v[108:109], 0
	v_mov_b64_e32 v[110:111], 0
	v_mov_b64_e32 v[116:117], 0
	v_mov_b64_e32 v[118:119], 0
	v_mov_b64_e32 v[124:125], 0
	v_mov_b64_e32 v[126:127], 0
	v_mov_b64_e32 v[128:129], 0
	v_mov_b64_e32 v[130:131], 0
	v_mov_b64_e32 v[132:133], 0
	v_mov_b64_e32 v[134:135], 0

; __device__ __forceinline__ float logsigmoid_f(float x) { return fminf(x, 0.0f) - __logf(1.0f + __expf(-fabsf(x))); }
; __device__ __forceinline__ void mlstm_out_unit(const KP& p, int j, int b, int n, int h, LAS unsigned char* lds, TilesML& pre, bool has_next, int b2, int n2, int h2) {
;     ...
;     const int t_ = tid >> 3, sg = tid & 7, c0 = h * 256 + sg * 32;
;     u32x2 cf[2][16];
;     { const u32x2* CS = (const u32x2*)GP(const bf16_t, WS_CS) + (size_t)ug * 16384 + lane;
; #pragma unroll
;       for (int j2 = 0; j2 < 2; ++j2)
; #pragma unroll
;           for (int dt = 0; dt < 16; ++dt) cf[j2][dt] = CS[(dt * 16 + 2 * wave + j2) * 64]; }
;     if (wave == 0) { const int t = lane; const float iv = pre.iv, lf = logsigmoid_f(pre.gf);
.LBB0_1377:
	s_bfe_u32 s24, s19, 0x70002
	s_and_b32 s0, s19, 0xfffffe00
	s_lshl_b32 s1, s24, 2
	s_and_b32 s23, s19, 3
	s_or_b32 s0, s1, s0
	s_or_b32 s0, s0, s23
	v_mov_b32_e32 v152, v0
	s_ashr_i32 s1, s0, 31
	s_lshl_b64 s[0:1], s[0:1], 17
	v_ashrrev_i32_e32 v56, 6, v152
	v_readlane_b32 s4, v252, 45
	v_and_b32_e32 v194, 63, v152
	v_readfirstlane_b32 s22, v56
	s_add_u32 s0, s4, s0
	v_readlane_b32 s4, v252, 46
	s_addc_u32 s1, s4, s1
	v_lshlrev_b32_e32 v154, 3, v194
	v_mov_b32_e32 v155, v2
	s_lshl_b32 s16, s22, 7
	v_lshl_add_u64 v[36:37], s[0:1], 0, v[154:155]
	s_add_i32 s0, s16, 0x400
	s_ashr_i32 s1, s0, 31
	v_lshl_add_u64 v[58:59], s[0:1], 3, v[36:37]
	s_add_i32 s0, s16, 0x800
	s_ashr_i32 s1, s0, 31
	v_lshl_add_u64 v[60:61], s[0:1], 3, v[36:37]
	s_add_i32 s0, s16, 0xc00
	s_ashr_i32 s1, s0, 31
	v_lshl_add_u64 v[62:63], s[0:1], 3, v[36:37]
	s_add_i32 s0, s16, 0x1000
	s_ashr_i32 s1, s0, 31
	v_lshl_add_u64 v[64:65], s[0:1], 3, v[36:37]
	s_add_i32 s0, s16, 0x1400
	s_ashr_i32 s1, s0, 31
	v_lshl_add_u64 v[66:67], s[0:1], 3, v[36:37]
	s_add_i32 s0, s16, 0x1800
	s_ashr_i32 s1, s0, 31
	v_lshl_add_u64 v[68:69], s[0:1], 3, v[36:37]
	s_add_i32 s0, s16, 0x1c00
	s_ashr_i32 s1, s0, 31
	global_load_dwordx2 v[134:135], v[62:63], off
	global_load_dwordx2 v[120:121], v[64:65], off
	global_load_dwordx2 v[122:123], v[66:67], off
	global_load_dwordx2 v[112:113], v[68:69], off
	v_lshl_add_u64 v[62:63], s[0:1], 3, v[36:37]
	s_add_i32 s0, s16, 0x2000
	s_ashr_i32 s1, s0, 31
	v_lshl_add_u64 v[64:65], s[0:1], 3, v[36:37]
	s_add_i32 s0, s16, 0x2400
	s_ashr_i32 s1, s0, 31
	v_lshl_add_u64 v[66:67], s[0:1], 3, v[36:37]
	s_add_i32 s0, s16, 0x2800
	s_ashr_i32 s1, s0, 31
	v_lshl_add_u64 v[68:69], s[0:1], 3, v[36:37]
	s_add_i32 s0, s16, 0x2c00
	s_ashr_i32 s1, s0, 31
	global_load_dwordx2 v[114:115], v[62:63], off
	global_load_dwordx2 v[108:109], v[64:65], off
	global_load_dwordx2 v[110:111], v[66:67], off
	global_load_dwordx2 v[100:101], v[68:69], off
	v_lshl_add_u64 v[62:63], s[0:1], 3, v[36:37]
	s_add_i32 s0, s16, 0x3000
	s_ashr_i32 s1, s0, 31
	v_lshl_add_u64 v[64:65], s[0:1], 3, v[36:37]
	s_add_i32 s0, s16, 0x3400
	s_ashr_i32 s1, s0, 31
	v_lshl_add_u64 v[66:67], s[0:1], 3, v[36:37]
	s_add_i32 s0, s16, 0x3800
	s_ashr_i32 s1, s0, 31
	v_lshl_add_u64 v[68:69], s[0:1], 3, v[36:37]
	s_add_i32 s0, s16, 0x3c00
	s_ashr_i32 s1, s0, 31
	s_ashr_i32 s17, s16, 31
	global_load_dwordx2 v[102:103], v[62:63], off
	global_load_dwordx2 v[92:93], v[64:65], off
	global_load_dwordx2 v[94:95], v[66:67], off
	global_load_dwordx2 v[88:89], v[68:69], off
	v_lshl_add_u64 v[62:63], s[0:1], 3, v[36:37]
	s_add_i32 s0, s16, 0x440
	v_lshl_add_u64 v[38:39], s[16:17], 3, v[36:37]
	s_ashr_i32 s1, s0, 31
	global_load_dwordx2 v[148:149], v[38:39], off
	global_load_dwordx2 v[150:151], v[58:59], off
	global_load_dwordx2 v[132:133], v[60:61], off
	global_load_dwordx2 v[144:145], v[38:39], off offset:512
	v_lshl_add_u64 v[38:39], s[0:1], 3, v[36:37]
	s_add_i32 s0, s16, 0x840
	s_ashr_i32 s1, s0, 31
	v_lshl_add_u64 v[58:59], s[0:1], 3, v[36:37]
	s_add_i32 s0, s16, 0xc40
	s_ashr_i32 s1, s0, 31
	v_lshl_add_u64 v[60:61], s[0:1], 3, v[36:37]
	s_add_i32 s0, s16, 0x1040
	s_ashr_i32 s1, s0, 31
	global_load_dwordx2 v[90:91], v[62:63], off
	global_load_dwordx2 v[146:147], v[38:39], off
	global_load_dwordx2 v[140:141], v[58:59], off
	global_load_dwordx2 v[142:143], v[60:61], off
	v_lshl_add_u64 v[38:39], s[0:1], 3, v[36:37]
	s_add_i32 s0, s16, 0x1440
	s_ashr_i32 s1, s0, 31
	v_lshl_add_u64 v[58:59], s[0:1], 3, v[36:37]
	s_add_i32 s0, s16, 0x1840
	s_ashr_i32 s1, s0, 31
	v_lshl_add_u64 v[60:61], s[0:1], 3, v[36:37]
	s_add_i32 s0, s16, 0x1c40
	s_ashr_i32 s1, s0, 31
	v_lshl_add_u64 v[62:63], s[0:1], 3, v[36:37]
	s_add_i32 s0, s16, 0x2040
	s_ashr_i32 s1, s0, 31
	global_load_dwordx2 v[136:137], v[38:39], off
	global_load_dwordx2 v[138:139], v[58:59], off
	global_load_dwordx2 v[128:129], v[60:61], off
	global_load_dwordx2 v[130:131], v[62:63], off
	v_lshl_add_u64 v[38:39], s[0:1], 3, v[36:37]
	s_add_i32 s0, s16, 0x2440
	s_ashr_i32 s1, s0, 31
	v_lshl_add_u64 v[58:59], s[0:1], 3, v[36:37]
	s_add_i32 s0, s16, 0x2840
	s_ashr_i32 s1, s0, 31
	v_lshl_add_u64 v[60:61], s[0:1], 3, v[36:37]
	s_add_i32 s0, s16, 0x2c40
	s_ashr_i32 s1, s0, 31
	v_lshl_add_u64 v[62:63], s[0:1], 3, v[36:37]
	s_add_i32 s0, s16, 0x3040
	s_ashr_i32 s1, s0, 31
	global_load_dwordx2 v[124:125], v[38:39], off
	global_load_dwordx2 v[126:127], v[58:59], off
	global_load_dwordx2 v[116:117], v[60:61], off
	global_load_dwordx2 v[118:119], v[62:63], off
	v_lshl_add_u64 v[38:39], s[0:1], 3, v[36:37]
	s_add_i32 s0, s16, 0x3440
	s_ashr_i32 s1, s0, 31
	v_lshl_add_u64 v[58:59], s[0:1], 3, v[36:37]
	s_add_i32 s0, s16, 0x3840
	s_ashr_i32 s1, s0, 31
	v_lshl_add_u64 v[60:61], s[0:1], 3, v[36:37]
	s_add_i32 s0, s16, 0x3c40
	s_ashr_i32 s1, s0, 31
	v_lshl_add_u64 v[36:37], s[0:1], 3, v[36:37]
	global_load_dwordx2 v[104:105], v[38:39], off
	global_load_dwordx2 v[106:107], v[58:59], off
	global_load_dwordx2 v[96:97], v[60:61], off
	global_load_dwordx2 v[98:99], v[36:37], off
	s_cmp_lg_u32 s22, 0
	v_cmp_gt_u32_e32 vcc, 16, v194
	s_cbranch_scc1 .LBB0_1379
; #define LAS __attribute__((address_space(3)))
; __device__ __forceinline__ float logsigmoid_f(float x) { return fminf(x, 0.0f) - __logf(1.0f + __expf(-fabsf(x))); }
; __device__ __forceinline__ void mlstm_out_unit(const KP& p, int j, int b, int n, int h, LAS unsigned char* lds, TilesML& pre, bool has_next, int b2, int n2, int h2) {
;     ...
;     if (wave == 0) { const int t = lane; const float iv = pre.iv, lf = logsigmoid_f(pre.gf);
;         float bcum = lf;
; #pragma unroll
;         for (int o = 1; o < 64; o <<= 1) { const float v = __shfl_up(bcum, o); if (lane >= o) bcum += v; }
;         float pm = iv - bcum;
; #pragma unroll
;         for (int o = 1; o < 64; o <<= 1) { const float v = __shfl_up(pm, o); if (lane >= o) pm = fmaxf(pm, v); }
;         bc[t] = bcum; ig[t] = iv; ml[t] = bcum + pm; }
;     { LAS u32x4* dq = (LAS u32x4*)(Qs + t_ * 264 + sg * 32); LAS u32x4* dk = (LAS u32x4*)(Ks + t_ * 264 + sg * 32); LAS u32x4* dv = (LAS u32x4*)(Vs + t_ * 264 + sg * 32);
; #pragma unroll
;       for (int c = 0; c < 4; ++c) { dq[c] = pre.q[c]; dk[c] = pre.k[c]; dv[c] = pre.v[c]; }
;       if (tid < 256) nvec[tid] = pre.nv; }
;     const float m = pre.m;
;     __syncthreads();
	s_waitcnt vmcnt(32)
	v_mul_f32_e64 v36, |v186|, s81
	v_exp_f32_e32 v36, v36
	v_max_f32_e32 v37, v186, v186
	v_min_f32_e32 v37, 0, v37
	v_add_f32_e32 v36, 1.0, v36
	v_cmp_gt_f32_e64 s[0:1], s75, v36
	s_nop 1
	v_cndmask_b32_e64 v38, 0, 32, s[0:1]
	v_ldexp_f32 v36, v36, v38
	v_log_f32_e32 v36, v36
	v_cndmask_b32_e64 v39, 0, v236, s[0:1]
	v_and_b32_e32 v38, 64, v235
	v_mul_f32_e32 v57, 0x3f317217, v36
	v_fma_f32 v57, v36, s15, -v57
	v_fmac_f32_e32 v57, 0x3377d1cf, v36
	v_fmac_f32_e32 v57, 0x3f317217, v36
	v_cmp_lt_f32_e64 s[0:1], |v36|, s78
	s_nop 1
	v_cndmask_b32_e64 v36, v36, v57, s[0:1]
	v_sub_f32_e32 v36, v36, v39
	v_sub_f32_e32 v36, v37, v36
	v_add_u32_e32 v37, -1, v235
	v_cmp_lt_i32_e64 s[0:1], v37, v38
	s_nop 1
	v_cndmask_b32_e64 v37, v37, v235, s[0:1]
	v_lshlrev_b32_e32 v37, 2, v37
	ds_bpermute_b32 v39, v37, v36
	v_cmp_eq_u32_e64 s[0:1], 0, v194
	s_waitcnt lgkmcnt(0)
	v_add_f32_e32 v39, v36, v39
	v_cndmask_b32_e64 v36, v39, v36, s[0:1]
	v_add_u32_e32 v39, -2, v235
	v_cmp_lt_i32_e64 s[4:5], v39, v38
	s_nop 1
	v_cndmask_b32_e64 v39, v39, v235, s[4:5]
	v_lshlrev_b32_e32 v39, 2, v39
	ds_bpermute_b32 v57, v39, v36
	v_cmp_gt_u32_e64 s[4:5], 2, v194
	s_waitcnt lgkmcnt(0)
	v_add_f32_e32 v57, v36, v57
	v_cndmask_b32_e64 v36, v57, v36, s[4:5]
	v_add_u32_e32 v57, -4, v235
	v_cmp_lt_i32_e64 s[6:7], v57, v38
	s_nop 1
	v_cndmask_b32_e64 v57, v57, v235, s[6:7]
	v_lshlrev_b32_e32 v57, 2, v57
	ds_bpermute_b32 v58, v57, v36
	v_cmp_gt_u32_e64 s[6:7], 4, v194
	s_waitcnt lgkmcnt(0)
	v_add_f32_e32 v58, v36, v58
	v_cndmask_b32_e64 v36, v58, v36, s[6:7]
	v_add_u32_e32 v58, -8, v235
	v_cmp_lt_i32_e64 s[8:9], v58, v38
	s_nop 1
	v_cndmask_b32_e64 v58, v58, v235, s[8:9]
	v_lshlrev_b32_e32 v58, 2, v58
	ds_bpermute_b32 v59, v58, v36
	v_cmp_gt_u32_e64 s[8:9], 8, v194
	s_waitcnt lgkmcnt(0)
	v_add_f32_e32 v59, v36, v59
	v_cndmask_b32_e64 v36, v59, v36, s[8:9]
	v_add_u32_e32 v59, -16, v235
	v_cmp_lt_i32_e64 s[10:11], v59, v38
	s_nop 1
	v_cndmask_b32_e64 v59, v59, v235, s[10:11]
	v_lshlrev_b32_e32 v59, 2, v59
	ds_bpermute_b32 v60, v59, v36
	s_waitcnt lgkmcnt(0)
	v_add_f32_e32 v60, v36, v60
	v_cndmask_b32_e32 v36, v60, v36, vcc
	v_subrev_u32_e32 v60, 32, v235
	v_cmp_lt_i32_e64 s[10:11], v60, v38
	s_nop 1
	v_cndmask_b32_e64 v38, v60, v235, s[10:11]
	v_lshlrev_b32_e32 v38, 2, v38
	ds_bpermute_b32 v60, v38, v36
	v_cmp_gt_u32_e64 s[10:11], 32, v194
	s_waitcnt lgkmcnt(0)
	v_add_f32_e32 v60, v36, v60
	v_cndmask_b32_e64 v36, v60, v36, s[10:11]
	v_sub_f32_e32 v60, v3, v36
	ds_bpermute_b32 v37, v37, v60
	s_waitcnt lgkmcnt(0)
	v_max_f32_e32 v37, v37, v37
	v_max_f32_e32 v37, v60, v37
	v_cndmask_b32_e64 v37, v37, v60, s[0:1]
	ds_bpermute_b32 v39, v39, v37
	s_waitcnt lgkmcnt(0)
	v_max_f32_e32 v39, v39, v39
	v_max_f32_e32 v39, v37, v39
	v_cndmask_b32_e64 v37, v39, v37, s[4:5]
	ds_bpermute_b32 v39, v57, v37
	v_lshl_add_u32 v57, v194, 2, 0
	s_waitcnt lgkmcnt(0)
	v_max_f32_e32 v39, v39, v39
	v_max_f32_e32 v39, v37, v39
	v_cndmask_b32_e64 v37, v39, v37, s[6:7]
	ds_bpermute_b32 v39, v58, v37
	v_add_u32_e32 v58, 0x18c00, v57
	s_waitcnt lgkmcnt(0)
	v_max_f32_e32 v39, v39, v39
	v_max_f32_e32 v39, v37, v39
	v_cndmask_b32_e64 v37, v39, v37, s[8:9]
	ds_bpermute_b32 v39, v59, v37
	s_waitcnt lgkmcnt(0)
	v_max_f32_e32 v39, v39, v39
	v_max_f32_e32 v39, v37, v39
	v_cndmask_b32_e32 v37, v39, v37, vcc
	ds_bpermute_b32 v38, v38, v37
	v_add_u32_e32 v39, 0x18d00, v57
	ds_write_b32 v39, v3
	ds_write_b32 v58, v36
	v_max_f32_e32 v39, v37, v37
	s_waitcnt lgkmcnt(2)
	v_max_f32_e32 v38, v38, v38
	v_max_f32_e32 v38, v39, v38
	v_cndmask_b32_e64 v37, v38, v37, s[10:11]
	v_add_f32_e32 v36, v36, v37
	v_add_u32_e32 v37, 0x18e00, v57
	ds_write_b32 v37, v36
.LBB0_1379:
	v_lshlrev_b32_e32 v190, 5, v152
	v_ashrrev_i32_e32 v188, 3, v152
	v_and_b32_e32 v189, 0xe0, v190
	v_mul_lo_u32 v36, v188, s79
	v_lshlrev_b32_e32 v37, 1, v189
	s_movk_i32 s0, 0x100
	v_add3_u32 v38, 0, v36, v37
	s_add_i32 s10, 0, 0x10800
	v_cmp_gt_i32_e64 s[4:5], s0, v152
	v_lshl_add_u32 v57, v152, 2, 0
	v_add3_u32 v36, s10, v36, v37
	s_waitcnt vmcnt(32)
	ds_write_b128 v38, v[16:19]
	ds_write_b128 v38, v[32:35] offset:33792
	ds_write_b128 v36, v[52:55]
	ds_write_b128 v38, v[12:15] offset:16
	ds_write_b128 v38, v[28:31] offset:33808
	ds_write_b128 v36, v[48:51] offset:16
	ds_write_b128 v38, v[8:11] offset:32
	ds_write_b128 v38, v[24:27] offset:33824
	ds_write_b128 v36, v[44:47] offset:32
	ds_write_b128 v38, v[4:7] offset:48
	ds_write_b128 v38, v[20:23] offset:33840
	ds_write_b128 v36, v[40:43] offset:48
	s_and_saveexec_b64 s[0:1], s[4:5]
	v_add_u32_e32 v36, 0x19f00, v57
	ds_write_b32 v36, v187
	s_or_b64 exec, exec, s[0:1]
	v_mul_u32_u24_e32 v36, 0x210, v194
	v_lshlrev_b32_e32 v37, 6, v56
	v_add3_u32 v36, 0, v36, v37
	s_waitcnt lgkmcnt(0)
	s_barrier
; #define LAS __attribute__((address_space(3)))
; __device__ __forceinline__ float bflo(unsigned w) { return __uint_as_float(w << 16); }
; __device__ __forceinline__ float bfhi(unsigned w) { return __uint_as_float(w & 0xffff0000u); }
; #define MFMA16(a, b, c) __builtin_amdgcn_mfma_f32_16x16x32_bf16((a), (b), (c), 0, 0, 0)
; __device__ __forceinline__ void mlstm_out_unit(const KP& p, int j, int b, int n, int h, LAS unsigned char* lds, TilesML& pre, bool has_next, int b2, int n2, int h2) {
;     ...
;     __syncthreads();
;     { const int t = tid & 63, part = tid >> 6; float s = 0.f;
; #pragma unroll
;       for (int dd = 0; dd < 32; dd += 2) { const unsigned w = *(const LAS unsigned*)(Qs + t * 264 + part * 32 + dd); s += bflo(w) * nvec[part * 32 + dd] + bfhi(w) * nvec[part * 32 + dd + 1]; }
;       qnp[part * 64 + t] = s; }
;     { const int tt = wave >> 1, stb = (wave & 1) * 2; f32x4 acc[2] = {F4ZERO, F4ZERO};
;       if (stb <= tt) {
; #pragma unroll
;           for (int ks = 0; ks < 8; ++ks) { const bf16x8 a = lds_frag(Qs, 264, tt * 16, ks * 32, lane);
; #pragma unroll
;               for (int s2 = 0; s2 < 2; ++s2) acc[s2] = MFMA16(a, lds_frag(Ks, 264, (stb + s2) * 16, ks * 32, lane), acc[s2]); } }
	ds_read_b128 v[58:61], v36
	v_lshl_add_u32 v37, v56, 7, 0
	v_add_u32_e32 v56, 0x19f00, v37
	ds_read_b128 v[62:65], v36 offset:16
	ds_read_b128 v[66:69], v36 offset:32
	ds_read_b128 v[70:73], v36 offset:48
	ds_read_b128 v[74:77], v56
	ds_read_b128 v[78:81], v56 offset:16
	ds_read_b128 v[82:85], v56 offset:32
	ds_read_b128 v[156:159], v56 offset:48
	s_waitcnt lgkmcnt(7)
	v_and_b32_e32 v37, 0xffff0000, v58
	v_lshlrev_b32_e32 v36, 16, v58
	s_waitcnt lgkmcnt(3)
	v_mul_f32_e32 v37, v75, v37
	v_fmac_f32_e32 v37, v74, v36
	v_and_b32_e32 v38, 0xffff0000, v59
	v_add_f32_e32 v36, 0, v37
	v_lshlrev_b32_e32 v37, 16, v59
	v_mul_f32_e32 v38, v77, v38
	v_fmac_f32_e32 v38, v76, v37
	v_add_f32_e32 v36, v36, v38
	v_and_b32_e32 v38, 0xffff0000, v60
	v_lshlrev_b32_e32 v37, 16, v60
	s_waitcnt lgkmcnt(2)
	v_mul_f32_e32 v38, v79, v38
	v_fmac_f32_e32 v38, v78, v37
	v_add_f32_e32 v36, v36, v38
	v_and_b32_e32 v38, 0xffff0000, v61
	v_lshlrev_b32_e32 v37, 16, v61
	v_mul_f32_e32 v38, v81, v38
	v_fmac_f32_e32 v38, v80, v37
	v_add_f32_e32 v60, v36, v38
	s_waitcnt lgkmcnt(1)
	v_mov_b32_e32 v36, v83
	v_lshlrev_b32_e32 v58, 16, v62
	v_and_b32_e32 v59, 0xffff0000, v63
	v_mov_b32_e32 v83, v85
	v_mov_b32_e32 v37, v84
	v_and_b32_e32 v38, 0xffff0000, v62
	v_lshlrev_b32_e32 v39, 16, v63
	v_pk_mul_f32 v[58:59], v[82:83], v[58:59]
	s_lshl_b32 s0, s22, 1
	v_pk_fma_f32 v[36:37], v[36:37], v[38:39], v[58:59]
	v_lshlrev_b32_e32 v58, 16, v64
	v_add_f32_e32 v36, v60, v36
	v_add_f32_e32 v74, v36, v37
	s_waitcnt lgkmcnt(0)
	v_mov_b32_e32 v36, v157
	v_and_b32_e32 v59, 0xffff0000, v65
	v_mov_b32_e32 v157, v159
	v_pk_mul_f32 v[62:63], v[156:157], v[58:59]
	ds_read_b128 v[58:61], v56 offset:64
	v_mov_b32_e32 v37, v158
	v_and_b32_e32 v38, 0xffff0000, v64
	v_lshlrev_b32_e32 v39, 16, v65
	v_pk_fma_f32 v[36:37], v[36:37], v[38:39], v[62:63]
	ds_read_b128 v[62:65], v56 offset:80
	v_add_f32_e32 v36, v74, v36
	v_add_f32_e32 v74, v36, v37
	s_waitcnt lgkmcnt(1)
	v_mov_b32_e32 v36, v59
	v_and_b32_e32 v38, 0xffff0000, v66
	v_lshlrev_b32_e32 v39, 16, v67
	v_lshlrev_b32_e32 v66, 16, v66
	v_and_b32_e32 v67, 0xffff0000, v67
	v_mov_b32_e32 v59, v61
	v_mov_b32_e32 v37, v60
	v_pk_mul_f32 v[58:59], v[58:59], v[66:67]
	v_and_b32_e32 v67, 0xffff0000, v71
	v_pk_fma_f32 v[36:37], v[36:37], v[38:39], v[58:59]
	v_lshlrev_b32_e32 v58, 16, v68
	v_add_f32_e32 v36, v74, v36
	v_add_f32_e32 v66, v36, v37
	s_waitcnt lgkmcnt(0)
	v_mov_b32_e32 v36, v63
	v_and_b32_e32 v59, 0xffff0000, v69
	v_mov_b32_e32 v63, v65
	v_pk_mul_f32 v[62:63], v[62:63], v[58:59]
	ds_read_b128 v[58:61], v56 offset:96
	v_mov_b32_e32 v37, v64
	v_and_b32_e32 v38, 0xffff0000, v68
	v_lshlrev_b32_e32 v39, 16, v69
	v_pk_fma_f32 v[36:37], v[36:37], v[38:39], v[62:63]
	ds_read_b128 v[62:65], v56 offset:112
	v_add_f32_e32 v36, v66, v36
	v_add_f32_e32 v68, v36, v37
	s_waitcnt lgkmcnt(1)
	v_mov_b32_e32 v36, v59
	v_lshlrev_b32_e32 v66, 16, v70
	v_mov_b32_e32 v59, v61
	v_mov_b32_e32 v37, v60
	v_and_b32_e32 v38, 0xffff0000, v70
	v_lshlrev_b32_e32 v39, 16, v71
	v_pk_mul_f32 v[58:59], v[58:59], v[66:67]
	s_ashr_i32 s6, s22, 1
	v_pk_fma_f32 v[36:37], v[36:37], v[38:39], v[58:59]
	v_lshlrev_b32_e32 v58, 16, v72
	v_add_f32_e32 v36, v68, v36
	v_add_f32_e32 v56, v36, v37
	s_waitcnt lgkmcnt(0)
	v_mov_b32_e32 v36, v63
	v_and_b32_e32 v59, 0xffff0000, v73
	v_mov_b32_e32 v63, v65
	v_mov_b32_e32 v37, v64
	v_and_b32_e32 v38, 0xffff0000, v72
	v_lshlrev_b32_e32 v39, 16, v73
	v_pk_mul_f32 v[58:59], v[62:63], v[58:59]
	s_and_b32 s8, s0, 2
	v_pk_fma_f32 v[36:37], v[36:37], v[38:39], v[58:59]
	s_mov_b64 s[0:1], -1
	v_add_f32_e32 v36, v56, v36
	v_add_f32_e32 v36, v36, v37
	v_add_u32_e32 v37, 0x18f00, v57
	s_cmp_le_i32 s8, s6
	v_and_b32_e32 v192, 48, v152
	v_and_b32_e32 v64, 15, v152
	ds_write_b32 v37, v36
	s_cbranch_scc0 .LBB0_1383
	s_lshl_b32 s7, s6, 4
	v_and_b32_e32 v193, 15, v152
	v_or_b32_e32 v37, s7, v193
	v_add_u32_e32 v36, 0, v192
	v_mad_u64_u32 v[38:39], s[0:1], v37, s79, v[36:37]
	ds_read_b128 v[56:59], v38
	v_lshl_or_b32 v67, s8, 4, v193
	v_mad_u32_u24 v36, v67, s79, v36
	ds_read_b128 v[60:63], v36 offset:33792
	ds_read_b128 v[68:71], v36 offset:42240
	s_mov_b64 s[0:1], 0
	s_waitcnt lgkmcnt(1)
	v_mfma_f32_16x16x32_bf16 v[60:63], v[56:59], v[60:63], 0
	v_mov_b32_e32 v65, s7
	s_waitcnt lgkmcnt(0)
	v_mfma_f32_16x16x32_bf16 v[56:59], v[56:59], v[68:71], 0
	ds_read_b128 v[68:71], v38 offset:64
	ds_read_b128 v[72:75], v36 offset:33856
	s_waitcnt lgkmcnt(0)
	v_mfma_f32_16x16x32_bf16 v[60:63], v[68:71], v[72:75], v[60:63]
	ds_read_b128 v[72:75], v36 offset:42304
	s_waitcnt lgkmcnt(0)
	v_mfma_f32_16x16x32_bf16 v[56:59], v[68:71], v[72:75], v[56:59]
	ds_read_b128 v[68:71], v38 offset:128
	ds_read_b128 v[72:75], v36 offset:33920
	s_waitcnt lgkmcnt(0)
	v_mfma_f32_16x16x32_bf16 v[60:63], v[68:71], v[72:75], v[60:63]
	ds_read_b128 v[72:75], v36 offset:42368
	s_waitcnt lgkmcnt(0)
	v_mfma_f32_16x16x32_bf16 v[56:59], v[68:71], v[72:75], v[56:59]
	ds_read_b128 v[68:71], v38 offset:192
	ds_read_b128 v[72:75], v36 offset:33984
	s_waitcnt lgkmcnt(0)
	v_mfma_f32_16x16x32_bf16 v[60:63], v[68:71], v[72:75], v[60:63]
	ds_read_b128 v[72:75], v36 offset:42432
	s_waitcnt lgkmcnt(0)
	v_mfma_f32_16x16x32_bf16 v[56:59], v[68:71], v[72:75], v[56:59]
	ds_read_b128 v[68:71], v38 offset:256
	ds_read_b128 v[72:75], v36 offset:34048
	s_waitcnt lgkmcnt(0)
	v_mfma_f32_16x16x32_bf16 v[60:63], v[68:71], v[72:75], v[60:63]
	ds_read_b128 v[72:75], v36 offset:42496
	s_waitcnt lgkmcnt(0)
	v_mfma_f32_16x16x32_bf16 v[56:59], v[68:71], v[72:75], v[56:59]
	ds_read_b128 v[68:71], v38 offset:320
	ds_read_b128 v[72:75], v36 offset:34112
	s_waitcnt lgkmcnt(0)
	v_mfma_f32_16x16x32_bf16 v[60:63], v[68:71], v[72:75], v[60:63]
	ds_read_b128 v[72:75], v36 offset:42560
	s_waitcnt lgkmcnt(0)
	v_mfma_f32_16x16x32_bf16 v[56:59], v[68:71], v[72:75], v[56:59]
	ds_read_b128 v[68:71], v38 offset:384
	ds_read_b128 v[72:75], v36 offset:34176
	s_waitcnt lgkmcnt(0)
	v_mfma_f32_16x16x32_bf16 v[60:63], v[68:71], v[72:75], v[60:63]
	ds_read_b128 v[72:75], v36 offset:42624
	s_waitcnt lgkmcnt(0)
	v_mfma_f32_16x16x32_bf16 v[56:59], v[68:71], v[72:75], v[56:59]
	ds_read_b128 v[68:71], v38 offset:448
	ds_read_b128 v[72:75], v36 offset:34240
	s_waitcnt lgkmcnt(0)
	v_mfma_f32_16x16x32_bf16 v[60:63], v[68:71], v[72:75], v[60:63]
	ds_read_b128 v[72:75], v36 offset:42688
	s_waitcnt lgkmcnt(0)
	v_mfma_f32_16x16x32_bf16 v[56:59], v[68:71], v[72:75], v[56:59]

; __device__ __forceinline__ void mlstm_out_load(const KP& p, TilesML& T, int b, int n, int h, int tid) {
;     const size_t ro = (size_t)(b * SEQ + n * 64 + (tid >> 3)) * 1024 + h * 256 + (tid & 7) * 32;
;     const u32x4* sq = (const u32x4*)(GP(const bf16_t, WS_Q) + ro); const u32x4* sk = (const u32x4*)(GP(const bf16_t, WS_KB) + ro); const u32x4* sv = (const u32x4*)(GP(const bf16_t, WS_V) + ro);
; #pragma unroll
;     for (int c = 0; c < 4; ++c) { T.q[c] = sq[c]; T.k[c] = sk[c]; T.v[c] = sv[c]; }
;     const int ug = (b * NCH + n) * 4 + h;
;     if (tid < 64) { const float* gt = GP(const float, WS_GATES) + (size_t)(b * SEQ + n * 64 + tid) * 8; T.iv = gt[h]; T.gf = gt[4 + h]; }
;     if (tid < 256) T.nv = GP(const float, WS_NS)[(size_t)ug * 256 + tid];
;     T.m = GP(const float, WS_MS)[ug];
; }
; __device__ __forceinline__ void mlstm_out_unit(const KP& p, int j, int b, int n, int h, LAS unsigned char* lds, TilesML& pre, bool has_next, int b2, int n2, int h2) {
;     ...
;     u32x4 xr[4], zq[4];
;     { const u32x4* sx = (const u32x4*)(GP(const bf16_t, WS_XC) + (size_t)(row0 + t_) * 1024 + c0); const u32x4* sz = (const u32x4*)(GP(const bf16_t, WS_HB) + (size_t)(row0 + t_) * OD_N + 1024 + c0);
; #pragma unroll
;       for (int c = 0; c < 4; ++c) { xr[c] = sx[c]; zq[c] = sz[c]; } }
;     if (has_next) mlstm_out_load(p, pre, b2, n2, h2, tid);
.LBB0_1422:
	s_or_b64 exec, exec, s[8:9]
	s_lshl_b64 s[4:5], s[6:7], 2
	v_readlane_b32 s6, v252, 49
	s_add_u32 s4, s6, s4
	v_readlane_b32 s6, v252, 50
	s_addc_u32 s5, s6, s5
	global_load_dword v185, v2, s[4:5]
	s_waitcnt vmcnt(21)
	s_branch .LBB0_1424
.LBB0_1423:
	s_waitcnt vmcnt(8)
	v_mov_b32_e32 v185, v191

; template <class Epi, class Sched, bool ALIGN_EPI = false, bool SP2 = false, bool ABLK = false, bool BBLK = false>
; __device__ __forceinline__ void gemm_phase(PG8_LAS unsigned char* lds, const Gemm g, const Sched& S, const Epi& E) {
;     ...
; #pragma unroll
;         for (int a = 0; a < 2; ++a)
; #pragma unroll
;             for (int b = 0; b < 2; ++b)
; #pragma unroll
;                 for (int m = 0; m < 4; ++m)
; #pragma unroll
;                     for (int n = 0; n < 2; ++n) acc[a][b][m][n] = (f32x4){0.f, 0.f, 0.f, 0.f};
;         cur = nxt; cA = nA; cB = nB; ++ui;
.LBB0_2110:
	s_ashr_i32 s17, s16, 31
	s_lshl_b64 s[12:13], s[16:17], 20
	s_add_u32 s18, s72, s12
	s_addc_u32 s19, s73, s13
	s_and_b64 s[12:13], s[4:5], exec
	s_cselect_b32 s12, s19, s23
	s_cselect_b32 s17, s18, s22
	s_ashr_i32 s11, s10, 31
	s_lshl_b64 s[20:21], s[10:11], 20
	v_readlane_b32 s26, v254, 3
	v_readlane_b32 s27, v254, 4
	s_add_u32 s20, s26, s20
	s_addc_u32 s21, s27, s21
	s_and_b64 s[26:27], s[4:5], exec
	s_cselect_b32 s11, s21, s25
	s_cselect_b32 s77, s20, s24
	s_add_u32 s22, s22, 0xc000
	s_addc_u32 s23, s23, 0
	s_add_u32 s82, s24, 0x10000
	v_mov_b32_e32 v4, 0
	s_addc_u32 vcc_lo, s25, 0
	s_mov_b32 s13, -2
	v_mov_b32_e32 v5, v4
	v_mov_b64_e32 v[6:7], 0
	v_mov_b64_e32 v[8:9], 0
	v_mov_b64_e32 v[10:11], 0
	v_mov_b64_e32 v[12:13], 0
	v_mov_b64_e32 v[14:15], 0
	v_mov_b64_e32 v[16:17], 0
	v_mov_b64_e32 v[18:19], 0
	v_mov_b64_e32 v[28:29], 0
	v_mov_b64_e32 v[30:31], 0
	v_mov_b64_e32 v[32:33], 0
	v_mov_b64_e32 v[34:35], 0
	v_mov_b64_e32 v[48:49], 0
	v_mov_b64_e32 v[50:51], 0
	v_mov_b64_e32 v[52:53], 0
	v_mov_b64_e32 v[54:55], 0
	v_mov_b64_e32 v[20:21], 0
	v_mov_b64_e32 v[22:23], 0
	v_mov_b64_e32 v[24:25], 0
	v_mov_b64_e32 v[26:27], 0
	v_mov_b64_e32 v[40:41], 0
	v_mov_b64_e32 v[42:43], 0
	v_mov_b64_e32 v[44:45], 0
	v_mov_b64_e32 v[46:47], 0
	v_mov_b64_e32 v[56:57], 0
	v_mov_b64_e32 v[58:59], 0
	v_mov_b64_e32 v[60:61], 0
	v_mov_b64_e32 v[62:63], 0
	v_mov_b64_e32 v[64:65], 0
	v_mov_b64_e32 v[66:67], 0
	v_mov_b64_e32 v[68:69], 0
	v_mov_b64_e32 v[70:71], 0
	v_mov_b64_e32 v[72:73], 0
	v_mov_b64_e32 v[74:75], 0
	v_mov_b64_e32 v[76:77], 0
	v_mov_b64_e32 v[78:79], 0
	v_mov_b64_e32 v[80:81], 0
	v_mov_b64_e32 v[82:83], 0
	v_mov_b64_e32 v[84:85], 0
	v_mov_b64_e32 v[86:87], 0
	v_mov_b64_e32 v[96:97], 0
	v_mov_b64_e32 v[98:99], 0
	v_mov_b64_e32 v[100:101], 0
	v_mov_b64_e32 v[102:103], 0
	v_mov_b64_e32 v[112:113], 0
	v_mov_b64_e32 v[114:115], 0
	v_mov_b64_e32 v[116:117], 0
	v_mov_b64_e32 v[118:119], 0
	v_mov_b64_e32 v[88:89], 0
	v_mov_b64_e32 v[90:91], 0
	v_mov_b64_e32 v[92:93], 0
	v_mov_b64_e32 v[94:95], 0
	v_mov_b64_e32 v[104:105], 0
	v_mov_b64_e32 v[106:107], 0
	v_mov_b64_e32 v[108:109], 0
	v_mov_b64_e32 v[110:111], 0
	v_mov_b64_e32 v[120:121], 0
	v_mov_b64_e32 v[122:123], 0
	v_mov_b64_e32 v[124:125], 0
	v_mov_b64_e32 v[126:127], 0
	v_mov_b64_e32 v[128:129], 0
	v_mov_b64_e32 v[130:131], 0
	v_mov_b64_e32 v[132:133], 0
	v_mov_b64_e32 v[134:135], 0
